# grid barrier flat release: all WGs poll the cross-XCD arrival counter; leader only wbl2 + one no-return add (drops TOPGEN/XGEN hops)
# speedup vs baseline: 1.0126x; 1.0126x over previous
; __device__ __forceinline__ unsigned xb_ld(unsigned* p)              { return __hip_atomic_load(p, __ATOMIC_RELAXED, __HIP_MEMORY_SCOPE_AGENT); }
; __device__ __forceinline__ unsigned xb_add(unsigned* p, unsigned v) { return __hip_atomic_fetch_add(p, v, __ATOMIC_RELAXED, __HIP_MEMORY_SCOPE_AGENT); }
; #define XB_SPIN(cond, bar) do { unsigned _sp = 0; while (cond) { __builtin_amdgcn_s_sleep(1); \
;     if ((++_sp & 255u) == 0u) { if (xb_ld(&(bar)[XB_TMO])) break; if (_sp > XB_SPIN_CAP) { atomicAdd(&(bar)[XB_TMO], 1u); break; } } } } while (0)
; __device__ __forceinline__ void xcd_barrier(const XcdBarrier& b, const bool is_t0) {
;     ...
;         unsigned nloc = b.st[0], nx = b.st[1];
;         if (nloc == 0u) { xcd_barrier_complete(bar, b.x, nloc, nx); b.st[0] = nloc; b.st[1] = nx; }
;         const unsigned old = xb_add(&bar[XB_XSUB(b.x)], 1u);
;         const unsigned gen = old / nloc;
;         if (old + 1u == (gen + 1u) * nloc) {
;             __builtin_amdgcn_fence(__ATOMIC_RELEASE, "agent");
;             asm volatile("s_waitcnt vmcnt(0)" ::: "memory");
;             const unsigned og = xb_add(&bar[XB_TOP], 1u);
;             const unsigned tg = og / nx;
;             if (og + 1u == (tg + 1u) * nx) xb_add(&bar[XB_TOPGEN], 1u);
;             else XB_SPIN(xb_ld(&bar[XB_TOPGEN]) == tg, bar);
;             __builtin_amdgcn_fence(__ATOMIC_ACQUIRE, "agent");
;             xb_add(&bar[XB_XGEN(b.x)], 1u);
;             asm volatile("s_waitcnt vmcnt(0)" ::: "memory");
;         } else {
;             XB_SPIN(xb_ld(&bar[XB_XGEN(b.x)]) == gen, bar);
;             __builtin_amdgcn_fence(__ATOMIC_ACQUIRE, "agent");
;             asm volatile("s_waitcnt vmcnt(0)" ::: "memory");
;         }
.LBB0_465:
	s_or_b64 exec, exec, s[18:19]
	v_cvt_f32_u32_e32 v4, v2
	s_waitcnt vmcnt(0)
	v_readfirstlane_b32 s8, v3
	v_sub_u32_e32 v3, 0, v2
	v_rcp_iflag_f32_e32 v4, v4
	v_add_u32_e32 v5, s8, v1
	v_mul_f32_e32 v4, 0x4f7ffffe, v4
	v_cvt_u32_f32_e32 v4, v4
	v_mul_lo_u32 v1, v3, v4
	v_mul_hi_u32 v1, v4, v1
	v_add_u32_e32 v1, v4, v1
	v_mul_hi_u32 v1, v5, v1
	v_mul_lo_u32 v3, v1, v2
	v_sub_u32_e32 v3, v5, v3
	v_add_u32_e32 v4, 1, v1
	v_cmp_ge_u32_e32 vcc, v3, v2
	s_nop 1
	v_cndmask_b32_e32 v1, v1, v4, vcc
	v_sub_u32_e32 v4, v3, v2
	v_cndmask_b32_e32 v3, v3, v4, vcc
	v_add_u32_e32 v4, 1, v1
	v_cmp_ge_u32_e32 vcc, v3, v2
	v_add_u32_e32 v3, 1, v5
	s_nop 0
	v_cndmask_b32_e32 v1, v1, v4, vcc
	v_mul_lo_u32 v4, v2, v1
	v_add_u32_e32 v2, v4, v2
	v_cmp_ne_u32_e32 vcc, v3, v2
	s_waitcnt lgkmcnt(0)
	v_mad_u32_u24 v4, v1, v0, v0
	s_cbranch_vccnz .Lxb1_poll
	buffer_wbl2 sc1
	s_waitcnt vmcnt(0)
	global_atomic_add v202, v203, s[74:75] offset:1024
.Lxb1_poll:
	s_movk_i32 s18, 0x4000
.Lxb1_spin:
	global_load_dword v5, v202, s[74:75] offset:1024 sc1
	s_waitcnt vmcnt(0)
	v_sub_u32_e32 v5, v5, v4
	v_cmp_gt_i32_e32 vcc, 0, v5
	s_cbranch_vccz .Lxb1_done
	s_sleep 1
	s_add_i32 s18, s18, -1
	s_cmp_lg_u32 s18, 0
	s_cbranch_scc1 .Lxb1_spin
.Lxb1_done:
	buffer_inv sc1
	s_waitcnt vmcnt(0)

; __device__ __forceinline__ unsigned xb_ld(unsigned* p)              { return __hip_atomic_load(p, __ATOMIC_RELAXED, __HIP_MEMORY_SCOPE_AGENT); }
; __device__ __forceinline__ unsigned xb_add(unsigned* p, unsigned v) { return __hip_atomic_fetch_add(p, v, __ATOMIC_RELAXED, __HIP_MEMORY_SCOPE_AGENT); }
; #define XB_SPIN(cond, bar) do { unsigned _sp = 0; while (cond) { __builtin_amdgcn_s_sleep(1); \
;     if ((++_sp & 255u) == 0u) { if (xb_ld(&(bar)[XB_TMO])) break; if (_sp > XB_SPIN_CAP) { atomicAdd(&(bar)[XB_TMO], 1u); break; } } } } while (0)
; __device__ __forceinline__ void xcd_barrier(const XcdBarrier& b, const bool is_t0) {
;     ...
;         unsigned nloc = b.st[0], nx = b.st[1];
;         if (nloc == 0u) { xcd_barrier_complete(bar, b.x, nloc, nx); b.st[0] = nloc; b.st[1] = nx; }
;         const unsigned old = xb_add(&bar[XB_XSUB(b.x)], 1u);
;         const unsigned gen = old / nloc;
;         if (old + 1u == (gen + 1u) * nloc) {
;             __builtin_amdgcn_fence(__ATOMIC_RELEASE, "agent");
;             asm volatile("s_waitcnt vmcnt(0)" ::: "memory");
;             const unsigned og = xb_add(&bar[XB_TOP], 1u);
;             const unsigned tg = og / nx;
;             if (og + 1u == (tg + 1u) * nx) xb_add(&bar[XB_TOPGEN], 1u);
;             else XB_SPIN(xb_ld(&bar[XB_TOPGEN]) == tg, bar);
;             __builtin_amdgcn_fence(__ATOMIC_ACQUIRE, "agent");
;             xb_add(&bar[XB_XGEN(b.x)], 1u);
;             asm volatile("s_waitcnt vmcnt(0)" ::: "memory");
;         } else {
;             XB_SPIN(xb_ld(&bar[XB_XGEN(b.x)]) == gen, bar);
;             __builtin_amdgcn_fence(__ATOMIC_ACQUIRE, "agent");
;             asm volatile("s_waitcnt vmcnt(0)" ::: "memory");
;         }
.LBB0_618:
	s_or_b64 exec, exec, s[10:11]
	v_cvt_f32_u32_e32 v4, v2
	s_waitcnt vmcnt(0)
	v_readfirstlane_b32 s8, v3
	v_sub_u32_e32 v3, 0, v2
	v_rcp_iflag_f32_e32 v4, v4
	v_add_u32_e32 v5, s8, v1
	v_mul_f32_e32 v4, 0x4f7ffffe, v4
	v_cvt_u32_f32_e32 v4, v4
	v_mul_lo_u32 v1, v3, v4
	v_mul_hi_u32 v1, v4, v1
	v_add_u32_e32 v1, v4, v1
	v_mul_hi_u32 v1, v5, v1
	v_mul_lo_u32 v3, v1, v2
	v_sub_u32_e32 v3, v5, v3
	v_add_u32_e32 v4, 1, v1
	v_cmp_ge_u32_e32 vcc, v3, v2
	s_nop 1
	v_cndmask_b32_e32 v1, v1, v4, vcc
	v_sub_u32_e32 v4, v3, v2
	v_cndmask_b32_e32 v3, v3, v4, vcc
	v_add_u32_e32 v4, 1, v1
	v_cmp_ge_u32_e32 vcc, v3, v2
	v_add_u32_e32 v3, 1, v5
	s_nop 0
	v_cndmask_b32_e32 v1, v1, v4, vcc
	v_mul_lo_u32 v4, v2, v1
	v_add_u32_e32 v2, v4, v2
	v_cmp_ne_u32_e32 vcc, v3, v2
	s_waitcnt lgkmcnt(0)
	v_mad_u32_u24 v4, v1, v0, v0
	s_cbranch_vccnz .Lxb2_poll
	buffer_wbl2 sc1
	s_waitcnt vmcnt(0)
	global_atomic_add v202, v203, s[6:7] offset:1024
.Lxb2_poll:
	s_movk_i32 s10, 0x4000
.Lxb2_spin:
	global_load_dword v5, v202, s[6:7] offset:1024 sc1
	s_waitcnt vmcnt(0)
	v_sub_u32_e32 v5, v5, v4
	v_cmp_gt_i32_e32 vcc, 0, v5
	s_cbranch_vccz .Lxb2_done
	s_sleep 1
	s_add_i32 s10, s10, -1
	s_cmp_lg_u32 s10, 0
	s_cbranch_scc1 .Lxb2_spin
.Lxb2_done:
	buffer_inv sc1
	s_waitcnt vmcnt(0)
	s_branch .LBB0_10
